# grid barrier: all waiting workgroups poll the cross-XCD arrival counter for (generation+1)*nx (no release-generation hops), on top of the combination
# baseline (speedup 1.0000x reference)
; __device__ __forceinline__ unsigned xb_ld(unsigned* p)              { return __hip_atomic_load(p, __ATOMIC_RELAXED, __HIP_MEMORY_SCOPE_AGENT); }
; __device__ __forceinline__ unsigned xb_add(unsigned* p, unsigned v) { return __hip_atomic_fetch_add(p, v, __ATOMIC_RELAXED, __HIP_MEMORY_SCOPE_AGENT); }
; #define XB_SPIN(cond, bar) do { unsigned _sp = 0; while (cond) { __builtin_amdgcn_s_sleep(1); \
;     if ((++_sp & 255u) == 0u) { if (xb_ld(&(bar)[XB_TMO])) break; if (_sp > XB_SPIN_CAP) { atomicAdd(&(bar)[XB_TMO], 1u); break; } } } } while (0)
; __device__ __forceinline__ void xcd_barrier(const XcdBarrier& b) {
;     ...
;         const unsigned old = xb_add(&bar[XB_XSUB(b.x)], 1u);
;         const unsigned gen = old / nloc;
;         if (old + 1u == (gen + 1u) * nloc) {
;             __builtin_amdgcn_fence(__ATOMIC_RELEASE, "agent");
;             asm volatile("s_waitcnt vmcnt(0)" ::: "memory");
;             const unsigned og = xb_add(&bar[XB_TOP], 1u);
;             const unsigned tg = og / nx;
;             if (og + 1u == (tg + 1u) * nx) xb_add(&bar[XB_TOPGEN], 1u);
;             else XB_SPIN(xb_ld(&bar[XB_TOPGEN]) == tg, bar);
;             __builtin_amdgcn_fence(__ATOMIC_ACQUIRE, "agent");
;             xb_add(&bar[XB_XGEN(b.x)], 1u);
;             asm volatile("s_waitcnt vmcnt(0)" ::: "memory");
;         } else {
;             XB_SPIN(xb_ld(&bar[XB_XGEN(b.x)]) == gen, bar);
.LBB0_122:
	s_or_b64 exec, exec, s[12:13]
	v_cvt_f32_u32_e32 v4, v2
	s_waitcnt vmcnt(0)
	v_readfirstlane_b32 s3, v3
	v_sub_u32_e32 v3, 0, v2
	v_rcp_iflag_f32_e32 v4, v4
	v_add_u32_e32 v5, s3, v1
	v_mul_f32_e32 v4, 0x4f7ffffe, v4
	v_cvt_u32_f32_e32 v4, v4
	v_mul_lo_u32 v1, v3, v4
	v_mul_hi_u32 v1, v4, v1
	v_add_u32_e32 v1, v4, v1
	v_mul_hi_u32 v1, v5, v1
	v_mul_lo_u32 v3, v1, v2
	v_sub_u32_e32 v3, v5, v3
	v_add_u32_e32 v4, 1, v1
	v_cmp_ge_u32_e32 vcc, v3, v2
	s_nop 1
	v_cndmask_b32_e32 v1, v1, v4, vcc
	v_sub_u32_e32 v4, v3, v2
	v_cndmask_b32_e32 v3, v3, v4, vcc
	v_add_u32_e32 v4, 1, v1
	v_cmp_ge_u32_e32 vcc, v3, v2
	v_add_u32_e32 v3, 1, v5
	s_nop 0
	v_cndmask_b32_e32 v1, v1, v4, vcc
	v_mul_lo_u32 v4, v2, v1
	v_add_u32_e32 v2, v4, v2
	v_cmp_ne_u32_e32 vcc, v3, v2
	s_and_saveexec_b64 s[10:11], vcc
	s_xor_b64 s[10:11], exec, s[10:11]
	s_cbranch_execz .LBB0_136
	s_waitcnt lgkmcnt(0)
	v_add_u32_e32 v3, 1, v1
	v_mul_lo_u32 v3, v3, v0
	v_mov_b32_e32 v0, 0xcb500
	global_load_dword v0, v0, s[6:7] offset:-256 sc1
	s_add_u32 s16, s6, 0xcb500
	s_addc_u32 s17, s7, 0
	s_waitcnt vmcnt(0)
	v_cmp_lt_u32_e32 vcc, v0, v3
	s_and_saveexec_b64 s[12:13], vcc
	s_cbranch_execz .LBB0_135
	s_add_u32 s14, s6, 0xc8200
	s_addc_u32 s15, s7, 0
	s_mov_b32 s3, 1
	s_mov_b64 s[18:19], 0
	v_mov_b32_e32 v0, 0
	s_branch .LBB0_126

; __device__ __forceinline__ unsigned xb_ld(unsigned* p)              { return __hip_atomic_load(p, __ATOMIC_RELAXED, __HIP_MEMORY_SCOPE_AGENT); }
; #define XB_SPIN(cond, bar) do { unsigned _sp = 0; while (cond) { __builtin_amdgcn_s_sleep(1); \
;     if ((++_sp & 255u) == 0u) { if (xb_ld(&(bar)[XB_TMO])) break; if (_sp > XB_SPIN_CAP) { atomicAdd(&(bar)[XB_TMO], 1u); break; } } } } while (0)
; __device__ __forceinline__ void xcd_barrier(const XcdBarrier& b) {
;     ...
;             XB_SPIN(xb_ld(&bar[XB_XGEN(b.x)]) == gen, bar);
.LBB0_130:
	global_load_dword v2, v0, s[16:17] offset:-256 sc1
	s_add_i32 s3, s3, 1
	s_mov_b64 s[26:27], -1
	s_waitcnt vmcnt(0)
	v_cmp_ge_u32_e32 vcc, v2, v3
	s_orn2_b64 s[22:23], vcc, exec
	s_branch .LBB0_125

; __device__ __forceinline__ unsigned xb_ld(unsigned* p)              { return __hip_atomic_load(p, __ATOMIC_RELAXED, __HIP_MEMORY_SCOPE_AGENT); }
; __device__ __forceinline__ unsigned xb_add(unsigned* p, unsigned v) { return __hip_atomic_fetch_add(p, v, __ATOMIC_RELAXED, __HIP_MEMORY_SCOPE_AGENT); }
; #define XB_SPIN(cond, bar) do { unsigned _sp = 0; while (cond) { __builtin_amdgcn_s_sleep(1); \
;     if ((++_sp & 255u) == 0u) { if (xb_ld(&(bar)[XB_TMO])) break; if (_sp > XB_SPIN_CAP) { atomicAdd(&(bar)[XB_TMO], 1u); break; } } } } while (0)
; __device__ __forceinline__ void xcd_barrier(const XcdBarrier& b) {
;     ...
;             const unsigned og = xb_add(&bar[XB_TOP], 1u);
;             const unsigned tg = og / nx;
;             if (og + 1u == (tg + 1u) * nx) xb_add(&bar[XB_TOPGEN], 1u);
;             else XB_SPIN(xb_ld(&bar[XB_TOPGEN]) == tg, bar);
.LBB0_139:
	s_or_b64 exec, exec, s[12:13]
	v_cvt_f32_u32_e32 v3, v0
	s_waitcnt vmcnt(0)
	v_readfirstlane_b32 s3, v2
	s_add_u32 s12, s6, 0xcb500
	s_addc_u32 s13, s7, 0
	v_rcp_iflag_f32_e32 v3, v3
	v_add_u32_e32 v1, s3, v1
	v_add_u32_e32 v4, 1, v1
	s_mov_b64 s[14:15], -1
	v_mul_f32_e32 v2, 0x4f7ffffe, v3
	v_cvt_u32_f32_e32 v2, v2
	v_sub_u32_e32 v3, 0, v0
	v_mul_lo_u32 v3, v3, v2
	v_mul_hi_u32 v3, v2, v3
	v_add_u32_e32 v2, v2, v3
	v_mul_hi_u32 v2, v1, v2
	v_mul_lo_u32 v3, v2, v0
	v_sub_u32_e32 v1, v1, v3
	v_add_u32_e32 v5, 1, v2
	v_cmp_ge_u32_e32 vcc, v1, v0
	v_sub_u32_e32 v3, v1, v0
	s_nop 0
	v_cndmask_b32_e32 v2, v2, v5, vcc
	v_cndmask_b32_e32 v1, v1, v3, vcc
	v_add_u32_e32 v3, 1, v2
	v_cmp_ge_u32_e32 vcc, v1, v0
	s_nop 1
	v_cndmask_b32_e32 v2, v2, v3, vcc
	v_mul_lo_u32 v1, v0, v2
	v_add_u32_e32 v0, v1, v0
	v_cmp_ne_u32_e32 vcc, v4, v0
	v_mov_b32_e32 v3, v0
	v_mov_b64_e32 v[0:1], s[12:13]
	s_and_saveexec_b64 s[10:11], vcc
	s_cbranch_execz .LBB0_151
	v_mov_b32_e32 v0, 0
	global_load_dword v1, v0, s[12:13] offset:-256 sc1
	s_mov_b64 s[18:19], 0
	s_waitcnt vmcnt(0)
	v_cmp_lt_u32_e32 vcc, v1, v3
	s_and_saveexec_b64 s[16:17], vcc
	s_cbranch_execz .LBB0_150
	s_add_u32 s14, s6, 0xc8200
	s_addc_u32 s15, s7, 0
	s_mov_b32 s3, 1
	s_mov_b64 s[6:7], 0
	s_branch .LBB0_143

; __device__ __forceinline__ unsigned xb_ld(unsigned* p)              { return __hip_atomic_load(p, __ATOMIC_RELAXED, __HIP_MEMORY_SCOPE_AGENT); }
; #define XB_SPIN(cond, bar) do { unsigned _sp = 0; while (cond) { __builtin_amdgcn_s_sleep(1); \
;     if ((++_sp & 255u) == 0u) { if (xb_ld(&(bar)[XB_TMO])) break; if (_sp > XB_SPIN_CAP) { atomicAdd(&(bar)[XB_TMO], 1u); break; } } } } while (0)
; __device__ __forceinline__ void xcd_barrier(const XcdBarrier& b) {
;     ...
;             else XB_SPIN(xb_ld(&bar[XB_TOPGEN]) == tg, bar);
.LBB0_147:
	global_load_dword v1, v0, s[12:13] offset:-256 sc1
	s_add_i32 s3, s3, 1
	s_mov_b64 s[20:21], -1
	s_waitcnt vmcnt(0)
	v_cmp_ge_u32_e32 vcc, v1, v3
	s_orn2_b64 s[26:27], vcc, exec
	s_branch .LBB0_142

; __device__ __forceinline__ unsigned xb_ld(unsigned* p)              { return __hip_atomic_load(p, __ATOMIC_RELAXED, __HIP_MEMORY_SCOPE_AGENT); }
; __device__ __forceinline__ unsigned xb_add(unsigned* p, unsigned v) { return __hip_atomic_fetch_add(p, v, __ATOMIC_RELAXED, __HIP_MEMORY_SCOPE_AGENT); }
; #define XB_SPIN(cond, bar) do { unsigned _sp = 0; while (cond) { __builtin_amdgcn_s_sleep(1); \
;     if ((++_sp & 255u) == 0u) { if (xb_ld(&(bar)[XB_TMO])) break; if (_sp > XB_SPIN_CAP) { atomicAdd(&(bar)[XB_TMO], 1u); break; } } } } while (0)
; __device__ __forceinline__ void xcd_barrier(const XcdBarrier& b) {
;     ...
;         const unsigned old = xb_add(&bar[XB_XSUB(b.x)], 1u);
;         const unsigned gen = old / nloc;
;         if (old + 1u == (gen + 1u) * nloc) {
;             __builtin_amdgcn_fence(__ATOMIC_RELEASE, "agent");
;             asm volatile("s_waitcnt vmcnt(0)" ::: "memory");
;             const unsigned og = xb_add(&bar[XB_TOP], 1u);
;             const unsigned tg = og / nx;
;             if (og + 1u == (tg + 1u) * nx) xb_add(&bar[XB_TOPGEN], 1u);
;             else XB_SPIN(xb_ld(&bar[XB_TOPGEN]) == tg, bar);
;             __builtin_amdgcn_fence(__ATOMIC_ACQUIRE, "agent");
;             xb_add(&bar[XB_XGEN(b.x)], 1u);
;             asm volatile("s_waitcnt vmcnt(0)" ::: "memory");
;         } else {
;             XB_SPIN(xb_ld(&bar[XB_XGEN(b.x)]) == gen, bar);
.LBB0_257:
	s_or_b64 exec, exec, s[12:13]
	v_cvt_f32_u32_e32 v4, v2
	s_waitcnt vmcnt(0)
	v_readfirstlane_b32 s3, v3
	v_sub_u32_e32 v3, 0, v2
	v_rcp_iflag_f32_e32 v4, v4
	v_add_u32_e32 v5, s3, v1
	v_mul_f32_e32 v4, 0x4f7ffffe, v4
	v_cvt_u32_f32_e32 v4, v4
	v_mul_lo_u32 v1, v3, v4
	v_mul_hi_u32 v1, v4, v1
	v_add_u32_e32 v1, v4, v1
	v_mul_hi_u32 v1, v5, v1
	v_mul_lo_u32 v3, v1, v2
	v_sub_u32_e32 v3, v5, v3
	v_add_u32_e32 v4, 1, v1
	v_cmp_ge_u32_e32 vcc, v3, v2
	s_nop 1
	v_cndmask_b32_e32 v1, v1, v4, vcc
	v_sub_u32_e32 v4, v3, v2
	v_cndmask_b32_e32 v3, v3, v4, vcc
	v_add_u32_e32 v4, 1, v1
	v_cmp_ge_u32_e32 vcc, v3, v2
	v_add_u32_e32 v3, 1, v5
	s_nop 0
	v_cndmask_b32_e32 v1, v1, v4, vcc
	v_mul_lo_u32 v4, v2, v1
	v_add_u32_e32 v2, v4, v2
	v_cmp_ne_u32_e32 vcc, v3, v2
	s_and_saveexec_b64 s[10:11], vcc
	s_xor_b64 s[10:11], exec, s[10:11]
	s_cbranch_execz .LBB0_271
	s_waitcnt lgkmcnt(0)
	v_add_u32_e32 v3, 1, v1
	v_mul_lo_u32 v3, v3, v0
	v_mov_b32_e32 v0, 0xcb500
	global_load_dword v0, v0, s[6:7] offset:-256 sc1
	s_add_u32 s18, s6, 0xcb500
	s_addc_u32 s19, s7, 0
	s_waitcnt vmcnt(0)
	v_cmp_lt_u32_e32 vcc, v0, v3
	s_and_saveexec_b64 s[12:13], vcc
	s_cbranch_execz .LBB0_270
	s_add_u32 s14, s6, 0xc8200
	s_addc_u32 s15, s7, 0
	s_mov_b32 s3, 1
	s_mov_b64 s[20:21], 0
	v_mov_b32_e32 v0, 0
	s_branch .LBB0_261

; __device__ __forceinline__ unsigned xb_ld(unsigned* p)              { return __hip_atomic_load(p, __ATOMIC_RELAXED, __HIP_MEMORY_SCOPE_AGENT); }
; #define XB_SPIN(cond, bar) do { unsigned _sp = 0; while (cond) { __builtin_amdgcn_s_sleep(1); \
;     if ((++_sp & 255u) == 0u) { if (xb_ld(&(bar)[XB_TMO])) break; if (_sp > XB_SPIN_CAP) { atomicAdd(&(bar)[XB_TMO], 1u); break; } } } } while (0)
; __device__ __forceinline__ void xcd_barrier(const XcdBarrier& b) {
;     ...
;             XB_SPIN(xb_ld(&bar[XB_XGEN(b.x)]) == gen, bar);
.LBB0_265:
	global_load_dword v2, v0, s[18:19] offset:-256 sc1
	s_add_i32 s3, s3, 1
	s_mov_b64 s[36:37], -1
	s_waitcnt vmcnt(0)
	v_cmp_ge_u32_e32 vcc, v2, v3
	s_orn2_b64 s[26:27], vcc, exec
	s_branch .LBB0_260

; __device__ __forceinline__ unsigned xb_ld(unsigned* p)              { return __hip_atomic_load(p, __ATOMIC_RELAXED, __HIP_MEMORY_SCOPE_AGENT); }
; __device__ __forceinline__ unsigned xb_add(unsigned* p, unsigned v) { return __hip_atomic_fetch_add(p, v, __ATOMIC_RELAXED, __HIP_MEMORY_SCOPE_AGENT); }
; #define XB_SPIN(cond, bar) do { unsigned _sp = 0; while (cond) { __builtin_amdgcn_s_sleep(1); \
;     if ((++_sp & 255u) == 0u) { if (xb_ld(&(bar)[XB_TMO])) break; if (_sp > XB_SPIN_CAP) { atomicAdd(&(bar)[XB_TMO], 1u); break; } } } } while (0)
; __device__ __forceinline__ void xcd_barrier(const XcdBarrier& b) {
;     ...
;             const unsigned og = xb_add(&bar[XB_TOP], 1u);
;             const unsigned tg = og / nx;
;             if (og + 1u == (tg + 1u) * nx) xb_add(&bar[XB_TOPGEN], 1u);
;             else XB_SPIN(xb_ld(&bar[XB_TOPGEN]) == tg, bar);
.LBB0_274:
	s_or_b64 exec, exec, s[12:13]
	v_cvt_f32_u32_e32 v3, v0
	s_waitcnt vmcnt(0)
	v_readfirstlane_b32 s3, v2
	s_add_u32 s12, s6, 0xcb500
	s_addc_u32 s13, s7, 0
	v_rcp_iflag_f32_e32 v3, v3
	v_add_u32_e32 v1, s3, v1
	v_add_u32_e32 v4, 1, v1
	s_mov_b64 s[14:15], -1
	v_mul_f32_e32 v2, 0x4f7ffffe, v3
	v_cvt_u32_f32_e32 v2, v2
	v_sub_u32_e32 v3, 0, v0
	v_mul_lo_u32 v3, v3, v2
	v_mul_hi_u32 v3, v2, v3
	v_add_u32_e32 v2, v2, v3
	v_mul_hi_u32 v2, v1, v2
	v_mul_lo_u32 v3, v2, v0
	v_sub_u32_e32 v1, v1, v3
	v_add_u32_e32 v5, 1, v2
	v_cmp_ge_u32_e32 vcc, v1, v0
	v_sub_u32_e32 v3, v1, v0
	s_nop 0
	v_cndmask_b32_e32 v2, v2, v5, vcc
	v_cndmask_b32_e32 v1, v1, v3, vcc
	v_add_u32_e32 v3, 1, v2
	v_cmp_ge_u32_e32 vcc, v1, v0
	s_nop 1
	v_cndmask_b32_e32 v2, v2, v3, vcc
	v_mul_lo_u32 v1, v0, v2
	v_add_u32_e32 v0, v1, v0
	v_cmp_ne_u32_e32 vcc, v4, v0
	v_mov_b32_e32 v3, v0
	v_mov_b64_e32 v[0:1], s[12:13]
	s_and_saveexec_b64 s[10:11], vcc
	s_cbranch_execz .LBB0_286
	v_mov_b32_e32 v0, 0
	global_load_dword v1, v0, s[12:13] offset:-256 sc1
	s_mov_b64 s[20:21], 0
	s_waitcnt vmcnt(0)
	v_cmp_lt_u32_e32 vcc, v1, v3
	s_and_saveexec_b64 s[18:19], vcc
	s_cbranch_execz .LBB0_285
	s_add_u32 s14, s6, 0xc8200
	s_addc_u32 s15, s7, 0
	s_mov_b32 s3, 1
	s_mov_b64 s[6:7], 0
	s_branch .LBB0_278

; __device__ __forceinline__ unsigned xb_ld(unsigned* p)              { return __hip_atomic_load(p, __ATOMIC_RELAXED, __HIP_MEMORY_SCOPE_AGENT); }
; #define XB_SPIN(cond, bar) do { unsigned _sp = 0; while (cond) { __builtin_amdgcn_s_sleep(1); \
;     if ((++_sp & 255u) == 0u) { if (xb_ld(&(bar)[XB_TMO])) break; if (_sp > XB_SPIN_CAP) { atomicAdd(&(bar)[XB_TMO], 1u); break; } } } } while (0)
; __device__ __forceinline__ void xcd_barrier(const XcdBarrier& b) {
;     ...
;             else XB_SPIN(xb_ld(&bar[XB_TOPGEN]) == tg, bar);
.LBB0_282:
	global_load_dword v1, v0, s[12:13] offset:-256 sc1
	s_add_i32 s3, s3, 1
	s_mov_b64 s[22:23], -1
	s_waitcnt vmcnt(0)
	v_cmp_ge_u32_e32 vcc, v1, v3
	s_orn2_b64 s[36:37], vcc, exec
	s_branch .LBB0_277

; __device__ __forceinline__ unsigned xb_ld(unsigned* p)              { return __hip_atomic_load(p, __ATOMIC_RELAXED, __HIP_MEMORY_SCOPE_AGENT); }
; __device__ __forceinline__ unsigned xb_add(unsigned* p, unsigned v) { return __hip_atomic_fetch_add(p, v, __ATOMIC_RELAXED, __HIP_MEMORY_SCOPE_AGENT); }
; #define XB_SPIN(cond, bar) do { unsigned _sp = 0; while (cond) { __builtin_amdgcn_s_sleep(1); \
;     if ((++_sp & 255u) == 0u) { if (xb_ld(&(bar)[XB_TMO])) break; if (_sp > XB_SPIN_CAP) { atomicAdd(&(bar)[XB_TMO], 1u); break; } } } } while (0)
; __device__ __forceinline__ void xcd_barrier(const XcdBarrier& b) {
;     ...
;         const unsigned old = xb_add(&bar[XB_XSUB(b.x)], 1u);
;         const unsigned gen = old / nloc;
;         if (old + 1u == (gen + 1u) * nloc) {
;             __builtin_amdgcn_fence(__ATOMIC_RELEASE, "agent");
;             asm volatile("s_waitcnt vmcnt(0)" ::: "memory");
;             const unsigned og = xb_add(&bar[XB_TOP], 1u);
;             const unsigned tg = og / nx;
;             if (og + 1u == (tg + 1u) * nx) xb_add(&bar[XB_TOPGEN], 1u);
;             else XB_SPIN(xb_ld(&bar[XB_TOPGEN]) == tg, bar);
;             __builtin_amdgcn_fence(__ATOMIC_ACQUIRE, "agent");
;             xb_add(&bar[XB_XGEN(b.x)], 1u);
;             asm volatile("s_waitcnt vmcnt(0)" ::: "memory");
;         } else {
;             XB_SPIN(xb_ld(&bar[XB_XGEN(b.x)]) == gen, bar);
.LBB0_401:
	s_or_b64 exec, exec, s[12:13]
	v_cvt_f32_u32_e32 v4, v2
	s_waitcnt vmcnt(0)
	v_readfirstlane_b32 s3, v3
	v_sub_u32_e32 v3, 0, v2
	v_rcp_iflag_f32_e32 v4, v4
	v_add_u32_e32 v5, s3, v1
	v_mul_f32_e32 v4, 0x4f7ffffe, v4
	v_cvt_u32_f32_e32 v4, v4
	v_mul_lo_u32 v1, v3, v4
	v_mul_hi_u32 v1, v4, v1
	v_add_u32_e32 v1, v4, v1
	v_mul_hi_u32 v1, v5, v1
	v_mul_lo_u32 v3, v1, v2
	v_sub_u32_e32 v3, v5, v3
	v_add_u32_e32 v4, 1, v1
	v_cmp_ge_u32_e32 vcc, v3, v2
	s_nop 1
	v_cndmask_b32_e32 v1, v1, v4, vcc
	v_sub_u32_e32 v4, v3, v2
	v_cndmask_b32_e32 v3, v3, v4, vcc
	v_add_u32_e32 v4, 1, v1
	v_cmp_ge_u32_e32 vcc, v3, v2
	v_add_u32_e32 v3, 1, v5
	s_nop 0
	v_cndmask_b32_e32 v1, v1, v4, vcc
	v_mul_lo_u32 v4, v2, v1
	v_add_u32_e32 v2, v4, v2
	v_cmp_ne_u32_e32 vcc, v3, v2
	s_and_saveexec_b64 s[10:11], vcc
	s_xor_b64 s[10:11], exec, s[10:11]
	s_cbranch_execz .LBB0_415
	s_waitcnt lgkmcnt(0)
	v_add_u32_e32 v3, 1, v1
	v_mul_lo_u32 v3, v3, v0
	v_mov_b32_e32 v0, 0xcb500
	global_load_dword v0, v0, s[6:7] offset:-256 sc1
	s_add_u32 s20, s6, 0xcb500
	s_addc_u32 s21, s7, 0
	s_waitcnt vmcnt(0)
	v_cmp_lt_u32_e32 vcc, v0, v3
	s_and_saveexec_b64 s[12:13], vcc
	s_cbranch_execz .LBB0_414
	s_add_u32 s14, s6, 0xc8200
	s_addc_u32 s15, s7, 0
	s_mov_b32 s3, 1
	s_mov_b64 s[22:23], 0
	v_mov_b32_e32 v0, 0
	s_branch .LBB0_405

; __device__ __forceinline__ unsigned xb_ld(unsigned* p)              { return __hip_atomic_load(p, __ATOMIC_RELAXED, __HIP_MEMORY_SCOPE_AGENT); }
; #define XB_SPIN(cond, bar) do { unsigned _sp = 0; while (cond) { __builtin_amdgcn_s_sleep(1); \
;     if ((++_sp & 255u) == 0u) { if (xb_ld(&(bar)[XB_TMO])) break; if (_sp > XB_SPIN_CAP) { atomicAdd(&(bar)[XB_TMO], 1u); break; } } } } while (0)
; __device__ __forceinline__ void xcd_barrier(const XcdBarrier& b) {
;     ...
;             XB_SPIN(xb_ld(&bar[XB_XGEN(b.x)]) == gen, bar);
.LBB0_409:
	global_load_dword v2, v0, s[20:21] offset:-256 sc1
	s_add_i32 s3, s3, 1
	s_mov_b64 s[38:39], -1
	s_waitcnt vmcnt(0)
	v_cmp_ge_u32_e32 vcc, v2, v3
	s_orn2_b64 s[36:37], vcc, exec
	s_branch .LBB0_404

; __device__ __forceinline__ unsigned xb_ld(unsigned* p)              { return __hip_atomic_load(p, __ATOMIC_RELAXED, __HIP_MEMORY_SCOPE_AGENT); }
; __device__ __forceinline__ unsigned xb_add(unsigned* p, unsigned v) { return __hip_atomic_fetch_add(p, v, __ATOMIC_RELAXED, __HIP_MEMORY_SCOPE_AGENT); }
; #define XB_SPIN(cond, bar) do { unsigned _sp = 0; while (cond) { __builtin_amdgcn_s_sleep(1); \
;     if ((++_sp & 255u) == 0u) { if (xb_ld(&(bar)[XB_TMO])) break; if (_sp > XB_SPIN_CAP) { atomicAdd(&(bar)[XB_TMO], 1u); break; } } } } while (0)
; __device__ __forceinline__ void xcd_barrier(const XcdBarrier& b) {
;     ...
;             const unsigned og = xb_add(&bar[XB_TOP], 1u);
;             const unsigned tg = og / nx;
;             if (og + 1u == (tg + 1u) * nx) xb_add(&bar[XB_TOPGEN], 1u);
;             else XB_SPIN(xb_ld(&bar[XB_TOPGEN]) == tg, bar);
.LBB0_418:
	s_or_b64 exec, exec, s[12:13]
	v_cvt_f32_u32_e32 v3, v0
	s_waitcnt vmcnt(0)
	v_readfirstlane_b32 s3, v2
	s_add_u32 s12, s6, 0xcb500
	s_addc_u32 s13, s7, 0
	v_rcp_iflag_f32_e32 v3, v3
	v_add_u32_e32 v1, s3, v1
	v_add_u32_e32 v4, 1, v1
	s_mov_b64 s[14:15], -1
	v_mul_f32_e32 v2, 0x4f7ffffe, v3
	v_cvt_u32_f32_e32 v2, v2
	v_sub_u32_e32 v3, 0, v0
	v_mul_lo_u32 v3, v3, v2
	v_mul_hi_u32 v3, v2, v3
	v_add_u32_e32 v2, v2, v3
	v_mul_hi_u32 v2, v1, v2
	v_mul_lo_u32 v3, v2, v0
	v_sub_u32_e32 v1, v1, v3
	v_add_u32_e32 v5, 1, v2
	v_cmp_ge_u32_e32 vcc, v1, v0
	v_sub_u32_e32 v3, v1, v0
	s_nop 0
	v_cndmask_b32_e32 v2, v2, v5, vcc
	v_cndmask_b32_e32 v1, v1, v3, vcc
	v_add_u32_e32 v3, 1, v2
	v_cmp_ge_u32_e32 vcc, v1, v0
	s_nop 1
	v_cndmask_b32_e32 v2, v2, v3, vcc
	v_mul_lo_u32 v1, v0, v2
	v_add_u32_e32 v0, v1, v0
	v_cmp_ne_u32_e32 vcc, v4, v0
	v_mov_b32_e32 v3, v0
	v_mov_b64_e32 v[0:1], s[12:13]
	s_and_saveexec_b64 s[10:11], vcc
	s_cbranch_execz .LBB0_430
	v_mov_b32_e32 v0, 0
	global_load_dword v1, v0, s[12:13] offset:-256 sc1
	s_mov_b64 s[22:23], 0
	s_waitcnt vmcnt(0)
	v_cmp_lt_u32_e32 vcc, v1, v3
	s_and_saveexec_b64 s[20:21], vcc
	s_cbranch_execz .LBB0_429
	s_add_u32 s14, s6, 0xc8200
	s_addc_u32 s15, s7, 0
	s_mov_b32 s3, 1
	s_mov_b64 s[6:7], 0
	s_branch .LBB0_422

; __device__ __forceinline__ unsigned xb_ld(unsigned* p)              { return __hip_atomic_load(p, __ATOMIC_RELAXED, __HIP_MEMORY_SCOPE_AGENT); }
; #define XB_SPIN(cond, bar) do { unsigned _sp = 0; while (cond) { __builtin_amdgcn_s_sleep(1); \
;     if ((++_sp & 255u) == 0u) { if (xb_ld(&(bar)[XB_TMO])) break; if (_sp > XB_SPIN_CAP) { atomicAdd(&(bar)[XB_TMO], 1u); break; } } } } while (0)
; __device__ __forceinline__ void xcd_barrier(const XcdBarrier& b) {
;     ...
;             else XB_SPIN(xb_ld(&bar[XB_TOPGEN]) == tg, bar);
.LBB0_426:
	global_load_dword v1, v0, s[12:13] offset:-256 sc1
	s_add_i32 s3, s3, 1
	s_mov_b64 s[26:27], -1
	s_waitcnt vmcnt(0)
	v_cmp_ge_u32_e32 vcc, v1, v3
	s_orn2_b64 s[38:39], vcc, exec
	s_branch .LBB0_421

; __device__ __forceinline__ unsigned xb_ld(unsigned* p)              { return __hip_atomic_load(p, __ATOMIC_RELAXED, __HIP_MEMORY_SCOPE_AGENT); }
; __device__ __forceinline__ unsigned xb_add(unsigned* p, unsigned v) { return __hip_atomic_fetch_add(p, v, __ATOMIC_RELAXED, __HIP_MEMORY_SCOPE_AGENT); }
; #define XB_SPIN(cond, bar) do { unsigned _sp = 0; while (cond) { __builtin_amdgcn_s_sleep(1); \
;     if ((++_sp & 255u) == 0u) { if (xb_ld(&(bar)[XB_TMO])) break; if (_sp > XB_SPIN_CAP) { atomicAdd(&(bar)[XB_TMO], 1u); break; } } } } while (0)
; __device__ __forceinline__ void xcd_barrier(const XcdBarrier& b) {
;     ...
;         const unsigned old = xb_add(&bar[XB_XSUB(b.x)], 1u);
;         const unsigned gen = old / nloc;
;         if (old + 1u == (gen + 1u) * nloc) {
;             __builtin_amdgcn_fence(__ATOMIC_RELEASE, "agent");
;             asm volatile("s_waitcnt vmcnt(0)" ::: "memory");
;             const unsigned og = xb_add(&bar[XB_TOP], 1u);
;             const unsigned tg = og / nx;
;             if (og + 1u == (tg + 1u) * nx) xb_add(&bar[XB_TOPGEN], 1u);
;             else XB_SPIN(xb_ld(&bar[XB_TOPGEN]) == tg, bar);
;             __builtin_amdgcn_fence(__ATOMIC_ACQUIRE, "agent");
;             xb_add(&bar[XB_XGEN(b.x)], 1u);
;             asm volatile("s_waitcnt vmcnt(0)" ::: "memory");
;         } else {
;             XB_SPIN(xb_ld(&bar[XB_XGEN(b.x)]) == gen, bar);
.LBB0_865:
	s_or_b64 exec, exec, s[14:15]
	v_cvt_f32_u32_e32 v4, v2
	s_waitcnt vmcnt(0)
	v_readfirstlane_b32 s3, v3
	v_sub_u32_e32 v3, 0, v2
	v_rcp_iflag_f32_e32 v4, v4
	v_add_u32_e32 v5, s3, v1
	v_mul_f32_e32 v4, 0x4f7ffffe, v4
	v_cvt_u32_f32_e32 v4, v4
	v_mul_lo_u32 v1, v3, v4
	v_mul_hi_u32 v1, v4, v1
	v_add_u32_e32 v1, v4, v1
	v_mul_hi_u32 v1, v5, v1
	v_mul_lo_u32 v3, v1, v2
	v_sub_u32_e32 v3, v5, v3
	v_add_u32_e32 v4, 1, v1
	v_cmp_ge_u32_e32 vcc, v3, v2
	s_nop 1
	v_cndmask_b32_e32 v1, v1, v4, vcc
	v_sub_u32_e32 v4, v3, v2
	v_cndmask_b32_e32 v3, v3, v4, vcc
	v_add_u32_e32 v4, 1, v1
	v_cmp_ge_u32_e32 vcc, v3, v2
	v_add_u32_e32 v3, 1, v5
	s_nop 0
	v_cndmask_b32_e32 v1, v1, v4, vcc
	v_mul_lo_u32 v4, v2, v1
	v_add_u32_e32 v2, v4, v2
	v_cmp_ne_u32_e32 vcc, v3, v2
	s_and_saveexec_b64 s[6:7], vcc
	s_xor_b64 s[12:13], exec, s[6:7]
	s_cbranch_execz .LBB0_879
	s_waitcnt lgkmcnt(0)
	v_add_u32_e32 v3, 1, v1
	v_mul_lo_u32 v3, v3, v0
	v_mov_b32_e32 v0, 0xcb500
	global_load_dword v0, v0, s[8:9] offset:-256 sc1
	s_add_u32 s22, s8, 0xcb500
	s_addc_u32 s23, s9, 0
	s_waitcnt vmcnt(0)
	v_cmp_lt_u32_e32 vcc, v0, v3
	s_and_saveexec_b64 s[14:15], vcc
	s_cbranch_execz .LBB0_878
	s_add_u32 s20, s8, 0xc8200
	s_addc_u32 s21, s9, 0
	s_mov_b32 s3, 1
	s_mov_b64 s[26:27], 0
	v_mov_b32_e32 v0, 0
	s_branch .LBB0_869

; __device__ __forceinline__ unsigned xb_ld(unsigned* p)              { return __hip_atomic_load(p, __ATOMIC_RELAXED, __HIP_MEMORY_SCOPE_AGENT); }
; #define XB_SPIN(cond, bar) do { unsigned _sp = 0; while (cond) { __builtin_amdgcn_s_sleep(1); \
;     if ((++_sp & 255u) == 0u) { if (xb_ld(&(bar)[XB_TMO])) break; if (_sp > XB_SPIN_CAP) { atomicAdd(&(bar)[XB_TMO], 1u); break; } } } } while (0)
; __device__ __forceinline__ void xcd_barrier(const XcdBarrier& b) {
;     ...
;             XB_SPIN(xb_ld(&bar[XB_XGEN(b.x)]) == gen, bar);
.LBB0_873:
	global_load_dword v2, v0, s[22:23] offset:-256 sc1
	s_add_i32 s3, s3, 1
	s_mov_b64 s[40:41], -1
	s_waitcnt vmcnt(0)
	v_cmp_ge_u32_e32 vcc, v2, v3
	s_orn2_b64 s[38:39], vcc, exec
	s_branch .LBB0_868

; __device__ __forceinline__ unsigned xb_ld(unsigned* p)              { return __hip_atomic_load(p, __ATOMIC_RELAXED, __HIP_MEMORY_SCOPE_AGENT); }
; __device__ __forceinline__ unsigned xb_add(unsigned* p, unsigned v) { return __hip_atomic_fetch_add(p, v, __ATOMIC_RELAXED, __HIP_MEMORY_SCOPE_AGENT); }
; #define XB_SPIN(cond, bar) do { unsigned _sp = 0; while (cond) { __builtin_amdgcn_s_sleep(1); \
;     if ((++_sp & 255u) == 0u) { if (xb_ld(&(bar)[XB_TMO])) break; if (_sp > XB_SPIN_CAP) { atomicAdd(&(bar)[XB_TMO], 1u); break; } } } } while (0)
; __device__ __forceinline__ void xcd_barrier(const XcdBarrier& b) {
;     ...
;             const unsigned og = xb_add(&bar[XB_TOP], 1u);
;             const unsigned tg = og / nx;
;             if (og + 1u == (tg + 1u) * nx) xb_add(&bar[XB_TOPGEN], 1u);
;             else XB_SPIN(xb_ld(&bar[XB_TOPGEN]) == tg, bar);
.LBB0_882:
	s_or_b64 exec, exec, s[14:15]
	v_cvt_f32_u32_e32 v3, v0
	s_waitcnt vmcnt(0)
	v_readfirstlane_b32 s3, v2
	s_add_u32 s14, s8, 0xcb500
	s_addc_u32 s15, s9, 0
	v_rcp_iflag_f32_e32 v3, v3
	v_add_u32_e32 v1, s3, v1
	v_add_u32_e32 v4, 1, v1
	s_mov_b64 s[20:21], -1
	v_mul_f32_e32 v2, 0x4f7ffffe, v3
	v_cvt_u32_f32_e32 v2, v2
	v_sub_u32_e32 v3, 0, v0
	v_mul_lo_u32 v3, v3, v2
	v_mul_hi_u32 v3, v2, v3
	v_add_u32_e32 v2, v2, v3
	v_mul_hi_u32 v2, v1, v2
	v_mul_lo_u32 v3, v2, v0
	v_sub_u32_e32 v1, v1, v3
	v_add_u32_e32 v5, 1, v2
	v_cmp_ge_u32_e32 vcc, v1, v0
	v_sub_u32_e32 v3, v1, v0
	s_nop 0
	v_cndmask_b32_e32 v2, v2, v5, vcc
	v_cndmask_b32_e32 v1, v1, v3, vcc
	v_add_u32_e32 v3, 1, v2
	v_cmp_ge_u32_e32 vcc, v1, v0
	s_nop 1
	v_cndmask_b32_e32 v2, v2, v3, vcc
	v_mul_lo_u32 v1, v0, v2
	v_add_u32_e32 v0, v1, v0
	v_cmp_ne_u32_e32 vcc, v4, v0
	v_mov_b32_e32 v3, v0
	v_mov_b64_e32 v[0:1], s[14:15]
	s_and_saveexec_b64 s[12:13], vcc
	s_cbranch_execz .LBB0_894
	v_mov_b32_e32 v0, 0
	global_load_dword v1, v0, s[14:15] offset:-256 sc1
	s_mov_b64 s[26:27], 0
	s_waitcnt vmcnt(0)
	v_cmp_lt_u32_e32 vcc, v1, v3
	s_and_saveexec_b64 s[22:23], vcc
	s_cbranch_execz .LBB0_893
	s_add_u32 s20, s8, 0xc8200
	s_addc_u32 s21, s9, 0
	s_mov_b32 s3, 1
	s_mov_b64 s[8:9], 0
	s_branch .LBB0_886

; __device__ __forceinline__ unsigned xb_ld(unsigned* p)              { return __hip_atomic_load(p, __ATOMIC_RELAXED, __HIP_MEMORY_SCOPE_AGENT); }
; #define XB_SPIN(cond, bar) do { unsigned _sp = 0; while (cond) { __builtin_amdgcn_s_sleep(1); \
;     if ((++_sp & 255u) == 0u) { if (xb_ld(&(bar)[XB_TMO])) break; if (_sp > XB_SPIN_CAP) { atomicAdd(&(bar)[XB_TMO], 1u); break; } } } } while (0)
; __device__ __forceinline__ void xcd_barrier(const XcdBarrier& b) {
;     ...
;             else XB_SPIN(xb_ld(&bar[XB_TOPGEN]) == tg, bar);
.LBB0_890:
	global_load_dword v1, v0, s[14:15] offset:-256 sc1
	s_add_i32 s3, s3, 1
	s_mov_b64 s[36:37], -1
	s_waitcnt vmcnt(0)
	v_cmp_ge_u32_e32 vcc, v1, v3
	s_orn2_b64 s[40:41], vcc, exec
	s_branch .LBB0_885

; __device__ __forceinline__ unsigned xb_ld(unsigned* p)              { return __hip_atomic_load(p, __ATOMIC_RELAXED, __HIP_MEMORY_SCOPE_AGENT); }
; __device__ __forceinline__ unsigned xb_add(unsigned* p, unsigned v) { return __hip_atomic_fetch_add(p, v, __ATOMIC_RELAXED, __HIP_MEMORY_SCOPE_AGENT); }
; #define XB_SPIN(cond, bar) do { unsigned _sp = 0; while (cond) { __builtin_amdgcn_s_sleep(1); \
;     if ((++_sp & 255u) == 0u) { if (xb_ld(&(bar)[XB_TMO])) break; if (_sp > XB_SPIN_CAP) { atomicAdd(&(bar)[XB_TMO], 1u); break; } } } } while (0)
; __device__ __forceinline__ void xcd_barrier(const XcdBarrier& b) {
;     ...
;         const unsigned old = xb_add(&bar[XB_XSUB(b.x)], 1u);
;         const unsigned gen = old / nloc;
;         if (old + 1u == (gen + 1u) * nloc) {
;             __builtin_amdgcn_fence(__ATOMIC_RELEASE, "agent");
;             asm volatile("s_waitcnt vmcnt(0)" ::: "memory");
;             const unsigned og = xb_add(&bar[XB_TOP], 1u);
;             const unsigned tg = og / nx;
;             if (og + 1u == (tg + 1u) * nx) xb_add(&bar[XB_TOPGEN], 1u);
;             else XB_SPIN(xb_ld(&bar[XB_TOPGEN]) == tg, bar);
;             __builtin_amdgcn_fence(__ATOMIC_ACQUIRE, "agent");
;             xb_add(&bar[XB_XGEN(b.x)], 1u);
;             asm volatile("s_waitcnt vmcnt(0)" ::: "memory");
;         } else {
;             XB_SPIN(xb_ld(&bar[XB_XGEN(b.x)]) == gen, bar);
.LBB0_1006:
	s_or_b64 exec, exec, s[20:21]
	v_cvt_f32_u32_e32 v4, v2
	s_waitcnt vmcnt(0)
	v_readfirstlane_b32 s6, v3
	v_sub_u32_e32 v3, 0, v2
	v_rcp_iflag_f32_e32 v4, v4
	v_add_u32_e32 v5, s6, v1
	v_mul_f32_e32 v4, 0x4f7ffffe, v4
	v_cvt_u32_f32_e32 v4, v4
	v_mul_lo_u32 v1, v3, v4
	v_mul_hi_u32 v1, v4, v1
	v_add_u32_e32 v1, v4, v1
	v_mul_hi_u32 v1, v5, v1
	v_mul_lo_u32 v3, v1, v2
	v_sub_u32_e32 v3, v5, v3
	v_add_u32_e32 v4, 1, v1
	v_cmp_ge_u32_e32 vcc, v3, v2
	s_nop 1
	v_cndmask_b32_e32 v1, v1, v4, vcc
	v_sub_u32_e32 v4, v3, v2
	v_cndmask_b32_e32 v3, v3, v4, vcc
	v_add_u32_e32 v4, 1, v1
	v_cmp_ge_u32_e32 vcc, v3, v2
	v_add_u32_e32 v3, 1, v5
	s_nop 0
	v_cndmask_b32_e32 v1, v1, v4, vcc
	v_mul_lo_u32 v4, v2, v1
	v_add_u32_e32 v2, v4, v2
	v_cmp_ne_u32_e32 vcc, v3, v2
	s_and_saveexec_b64 s[6:7], vcc
	s_xor_b64 s[14:15], exec, s[6:7]
	s_cbranch_execz .LBB0_1020
	s_waitcnt lgkmcnt(0)
	v_add_u32_e32 v3, 1, v1
	v_mul_lo_u32 v3, v3, v0
	v_mov_b32_e32 v0, 0xcb500
	global_load_dword v0, v0, s[10:11] offset:-256 sc1
	s_add_u32 s26, s10, 0xcb500
	s_addc_u32 s27, s11, 0
	s_waitcnt vmcnt(0)
	v_cmp_lt_u32_e32 vcc, v0, v3
	s_and_saveexec_b64 s[20:21], vcc
	s_cbranch_execz .LBB0_1019
	s_add_u32 s22, s10, 0xc8200
	s_addc_u32 s23, s11, 0
	s_mov_b32 s6, 1
	s_mov_b64 s[36:37], 0
	v_mov_b32_e32 v0, 0
	s_branch .LBB0_1010

; __device__ __forceinline__ unsigned xb_ld(unsigned* p)              { return __hip_atomic_load(p, __ATOMIC_RELAXED, __HIP_MEMORY_SCOPE_AGENT); }
; #define XB_SPIN(cond, bar) do { unsigned _sp = 0; while (cond) { __builtin_amdgcn_s_sleep(1); \
;     if ((++_sp & 255u) == 0u) { if (xb_ld(&(bar)[XB_TMO])) break; if (_sp > XB_SPIN_CAP) { atomicAdd(&(bar)[XB_TMO], 1u); break; } } } } while (0)
; __device__ __forceinline__ void xcd_barrier(const XcdBarrier& b) {
;     ...
;             XB_SPIN(xb_ld(&bar[XB_XGEN(b.x)]) == gen, bar);
.LBB0_1014:
	global_load_dword v2, v0, s[26:27] offset:-256 sc1
	s_add_i32 s6, s6, 1
	s_mov_b64 s[42:43], -1
	s_waitcnt vmcnt(0)
	v_cmp_ge_u32_e32 vcc, v2, v3
	s_orn2_b64 s[40:41], vcc, exec
	s_branch .LBB0_1009

; __device__ __forceinline__ unsigned xb_ld(unsigned* p)              { return __hip_atomic_load(p, __ATOMIC_RELAXED, __HIP_MEMORY_SCOPE_AGENT); }
; __device__ __forceinline__ unsigned xb_add(unsigned* p, unsigned v) { return __hip_atomic_fetch_add(p, v, __ATOMIC_RELAXED, __HIP_MEMORY_SCOPE_AGENT); }
; #define XB_SPIN(cond, bar) do { unsigned _sp = 0; while (cond) { __builtin_amdgcn_s_sleep(1); \
;     if ((++_sp & 255u) == 0u) { if (xb_ld(&(bar)[XB_TMO])) break; if (_sp > XB_SPIN_CAP) { atomicAdd(&(bar)[XB_TMO], 1u); break; } } } } while (0)
; __device__ __forceinline__ void xcd_barrier(const XcdBarrier& b) {
;     ...
;             const unsigned og = xb_add(&bar[XB_TOP], 1u);
;             const unsigned tg = og / nx;
;             if (og + 1u == (tg + 1u) * nx) xb_add(&bar[XB_TOPGEN], 1u);
;             else XB_SPIN(xb_ld(&bar[XB_TOPGEN]) == tg, bar);
.LBB0_1023:
	s_or_b64 exec, exec, s[20:21]
	v_cvt_f32_u32_e32 v3, v0
	s_waitcnt vmcnt(0)
	v_readfirstlane_b32 s6, v2
	s_add_u32 s20, s10, 0xcb500
	s_addc_u32 s21, s11, 0
	v_rcp_iflag_f32_e32 v3, v3
	v_add_u32_e32 v1, s6, v1
	v_add_u32_e32 v4, 1, v1
	s_mov_b64 s[22:23], -1
	v_mul_f32_e32 v2, 0x4f7ffffe, v3
	v_cvt_u32_f32_e32 v2, v2
	v_sub_u32_e32 v3, 0, v0
	v_mul_lo_u32 v3, v3, v2
	v_mul_hi_u32 v3, v2, v3
	v_add_u32_e32 v2, v2, v3
	v_mul_hi_u32 v2, v1, v2
	v_mul_lo_u32 v3, v2, v0
	v_sub_u32_e32 v1, v1, v3
	v_add_u32_e32 v5, 1, v2
	v_cmp_ge_u32_e32 vcc, v1, v0
	v_sub_u32_e32 v3, v1, v0
	s_nop 0
	v_cndmask_b32_e32 v2, v2, v5, vcc
	v_cndmask_b32_e32 v1, v1, v3, vcc
	v_add_u32_e32 v3, 1, v2
	v_cmp_ge_u32_e32 vcc, v1, v0
	s_nop 1
	v_cndmask_b32_e32 v2, v2, v3, vcc
	v_mul_lo_u32 v1, v0, v2
	v_add_u32_e32 v0, v1, v0
	v_cmp_ne_u32_e32 vcc, v4, v0
	v_mov_b32_e32 v3, v0
	v_mov_b64_e32 v[0:1], s[20:21]
	s_and_saveexec_b64 s[14:15], vcc
	s_cbranch_execz .LBB0_1035
	v_mov_b32_e32 v0, 0
	global_load_dword v1, v0, s[20:21] offset:-256 sc1
	s_mov_b64 s[36:37], 0
	s_waitcnt vmcnt(0)
	v_cmp_lt_u32_e32 vcc, v1, v3
	s_and_saveexec_b64 s[26:27], vcc
	s_cbranch_execz .LBB0_1034
	s_add_u32 s22, s10, 0xc8200
	s_addc_u32 s23, s11, 0
	s_mov_b32 s6, 1
	s_mov_b64 s[10:11], 0
	s_branch .LBB0_1027

; __device__ __forceinline__ unsigned xb_ld(unsigned* p)              { return __hip_atomic_load(p, __ATOMIC_RELAXED, __HIP_MEMORY_SCOPE_AGENT); }
; #define XB_SPIN(cond, bar) do { unsigned _sp = 0; while (cond) { __builtin_amdgcn_s_sleep(1); \
;     if ((++_sp & 255u) == 0u) { if (xb_ld(&(bar)[XB_TMO])) break; if (_sp > XB_SPIN_CAP) { atomicAdd(&(bar)[XB_TMO], 1u); break; } } } } while (0)
; __device__ __forceinline__ void xcd_barrier(const XcdBarrier& b) {
;     ...
;             else XB_SPIN(xb_ld(&bar[XB_TOPGEN]) == tg, bar);
.LBB0_1031:
	global_load_dword v1, v0, s[20:21] offset:-256 sc1
	s_add_i32 s6, s6, 1
	s_mov_b64 s[38:39], -1
	s_waitcnt vmcnt(0)
	v_cmp_ge_u32_e32 vcc, v1, v3
	s_orn2_b64 s[42:43], vcc, exec
	s_branch .LBB0_1026

; __device__ __forceinline__ unsigned xb_ld(unsigned* p)              { return __hip_atomic_load(p, __ATOMIC_RELAXED, __HIP_MEMORY_SCOPE_AGENT); }
; __device__ __forceinline__ unsigned xb_add(unsigned* p, unsigned v) { return __hip_atomic_fetch_add(p, v, __ATOMIC_RELAXED, __HIP_MEMORY_SCOPE_AGENT); }
; #define XB_SPIN(cond, bar) do { unsigned _sp = 0; while (cond) { __builtin_amdgcn_s_sleep(1); \
;     if ((++_sp & 255u) == 0u) { if (xb_ld(&(bar)[XB_TMO])) break; if (_sp > XB_SPIN_CAP) { atomicAdd(&(bar)[XB_TMO], 1u); break; } } } } while (0)
; __device__ __forceinline__ void xcd_barrier(const XcdBarrier& b) {
;     ...
;         const unsigned old = xb_add(&bar[XB_XSUB(b.x)], 1u);
;         const unsigned gen = old / nloc;
;         if (old + 1u == (gen + 1u) * nloc) {
;             __builtin_amdgcn_fence(__ATOMIC_RELEASE, "agent");
;             asm volatile("s_waitcnt vmcnt(0)" ::: "memory");
;             const unsigned og = xb_add(&bar[XB_TOP], 1u);
;             const unsigned tg = og / nx;
;             if (og + 1u == (tg + 1u) * nx) xb_add(&bar[XB_TOPGEN], 1u);
;             else XB_SPIN(xb_ld(&bar[XB_TOPGEN]) == tg, bar);
;             __builtin_amdgcn_fence(__ATOMIC_ACQUIRE, "agent");
;             xb_add(&bar[XB_XGEN(b.x)], 1u);
;             asm volatile("s_waitcnt vmcnt(0)" ::: "memory");
;         } else {
;             XB_SPIN(xb_ld(&bar[XB_XGEN(b.x)]) == gen, bar);
.LBB0_1212:
	s_or_b64 exec, exec, s[20:21]
	v_cvt_f32_u32_e32 v4, v2
	s_waitcnt vmcnt(0)
	v_readfirstlane_b32 s6, v3
	v_sub_u32_e32 v3, 0, v2
	v_rcp_iflag_f32_e32 v4, v4
	v_add_u32_e32 v5, s6, v1
	v_mul_f32_e32 v4, 0x4f7ffffe, v4
	v_cvt_u32_f32_e32 v4, v4
	v_mul_lo_u32 v1, v3, v4
	v_mul_hi_u32 v1, v4, v1
	v_add_u32_e32 v1, v4, v1
	v_mul_hi_u32 v1, v5, v1
	v_mul_lo_u32 v3, v1, v2
	v_sub_u32_e32 v3, v5, v3
	v_add_u32_e32 v4, 1, v1
	v_cmp_ge_u32_e32 vcc, v3, v2
	s_nop 1
	v_cndmask_b32_e32 v1, v1, v4, vcc
	v_sub_u32_e32 v4, v3, v2
	v_cndmask_b32_e32 v3, v3, v4, vcc
	v_add_u32_e32 v4, 1, v1
	v_cmp_ge_u32_e32 vcc, v3, v2
	v_add_u32_e32 v3, 1, v5
	s_nop 0
	v_cndmask_b32_e32 v1, v1, v4, vcc
	v_mul_lo_u32 v4, v2, v1
	v_add_u32_e32 v2, v4, v2
	v_cmp_ne_u32_e32 vcc, v3, v2
	s_and_saveexec_b64 s[6:7], vcc
	s_xor_b64 s[18:19], exec, s[6:7]
	s_cbranch_execz .LBB0_1226
	s_waitcnt lgkmcnt(0)
	v_add_u32_e32 v3, 1, v1
	v_mul_lo_u32 v3, v3, v0
	v_mov_b32_e32 v0, 0xcb500
	global_load_dword v0, v0, s[12:13] offset:-256 sc1
	s_add_u32 s26, s12, 0xcb500
	s_addc_u32 s27, s13, 0
	s_waitcnt vmcnt(0)
	v_cmp_lt_u32_e32 vcc, v0, v3
	s_and_saveexec_b64 s[20:21], vcc
	s_cbranch_execz .LBB0_1225
	s_add_u32 s22, s12, 0xc8200
	s_addc_u32 s23, s13, 0
	s_mov_b32 s6, 1
	s_mov_b64 s[36:37], 0
	v_mov_b32_e32 v0, 0
	s_branch .LBB0_1216

; __device__ __forceinline__ unsigned xb_ld(unsigned* p)              { return __hip_atomic_load(p, __ATOMIC_RELAXED, __HIP_MEMORY_SCOPE_AGENT); }
; __device__ __forceinline__ unsigned xb_add(unsigned* p, unsigned v) { return __hip_atomic_fetch_add(p, v, __ATOMIC_RELAXED, __HIP_MEMORY_SCOPE_AGENT); }
; #define XB_SPIN(cond, bar) do { unsigned _sp = 0; while (cond) { __builtin_amdgcn_s_sleep(1); \
;     if ((++_sp & 255u) == 0u) { if (xb_ld(&(bar)[XB_TMO])) break; if (_sp > XB_SPIN_CAP) { atomicAdd(&(bar)[XB_TMO], 1u); break; } } } } while (0)
; __device__ __forceinline__ void xcd_barrier(const XcdBarrier& b) {
;     ...
;             const unsigned og = xb_add(&bar[XB_TOP], 1u);
;             const unsigned tg = og / nx;
;             if (og + 1u == (tg + 1u) * nx) xb_add(&bar[XB_TOPGEN], 1u);
;             else XB_SPIN(xb_ld(&bar[XB_TOPGEN]) == tg, bar);
.LBB0_1229:
	s_or_b64 exec, exec, s[20:21]
	v_cvt_f32_u32_e32 v3, v0
	s_waitcnt vmcnt(0)
	v_readfirstlane_b32 s6, v2
	s_add_u32 s20, s12, 0xcb500
	s_addc_u32 s21, s13, 0
	v_rcp_iflag_f32_e32 v3, v3
	v_add_u32_e32 v1, s6, v1
	v_add_u32_e32 v4, 1, v1
	s_mov_b64 s[22:23], -1
	v_mul_f32_e32 v2, 0x4f7ffffe, v3
	v_cvt_u32_f32_e32 v2, v2
	v_sub_u32_e32 v3, 0, v0
	v_mul_lo_u32 v3, v3, v2
	v_mul_hi_u32 v3, v2, v3
	v_add_u32_e32 v2, v2, v3
	v_mul_hi_u32 v2, v1, v2
	v_mul_lo_u32 v3, v2, v0
	v_sub_u32_e32 v1, v1, v3
	v_add_u32_e32 v5, 1, v2
	v_cmp_ge_u32_e32 vcc, v1, v0
	v_sub_u32_e32 v3, v1, v0
	s_nop 0
	v_cndmask_b32_e32 v2, v2, v5, vcc
	v_cndmask_b32_e32 v1, v1, v3, vcc
	v_add_u32_e32 v3, 1, v2
	v_cmp_ge_u32_e32 vcc, v1, v0
	s_nop 1
	v_cndmask_b32_e32 v2, v2, v3, vcc
	v_mul_lo_u32 v1, v0, v2
	v_add_u32_e32 v0, v1, v0
	v_cmp_ne_u32_e32 vcc, v4, v0
	v_mov_b32_e32 v3, v0
	v_mov_b64_e32 v[0:1], s[20:21]
	s_and_saveexec_b64 s[18:19], vcc
	s_cbranch_execz .LBB0_1241
	v_mov_b32_e32 v0, 0
	global_load_dword v1, v0, s[20:21] offset:-256 sc1
	s_mov_b64 s[36:37], 0
	s_waitcnt vmcnt(0)
	v_cmp_lt_u32_e32 vcc, v1, v3
	s_and_saveexec_b64 s[26:27], vcc
	s_cbranch_execz .LBB0_1240
	s_add_u32 s22, s12, 0xc8200
	s_addc_u32 s23, s13, 0
	s_mov_b32 s6, 1
	s_mov_b64 s[12:13], 0
	s_branch .LBB0_1233

; __device__ __forceinline__ unsigned xb_ld(unsigned* p)              { return __hip_atomic_load(p, __ATOMIC_RELAXED, __HIP_MEMORY_SCOPE_AGENT); }
; __device__ __forceinline__ unsigned xb_add(unsigned* p, unsigned v) { return __hip_atomic_fetch_add(p, v, __ATOMIC_RELAXED, __HIP_MEMORY_SCOPE_AGENT); }
; #define XB_SPIN(cond, bar) do { unsigned _sp = 0; while (cond) { __builtin_amdgcn_s_sleep(1); \
;     if ((++_sp & 255u) == 0u) { if (xb_ld(&(bar)[XB_TMO])) break; if (_sp > XB_SPIN_CAP) { atomicAdd(&(bar)[XB_TMO], 1u); break; } } } } while (0)
; __device__ __forceinline__ void xcd_barrier(const XcdBarrier& b) {
;     ...
;         const unsigned old = xb_add(&bar[XB_XSUB(b.x)], 1u);
;         const unsigned gen = old / nloc;
;         if (old + 1u == (gen + 1u) * nloc) {
;             __builtin_amdgcn_fence(__ATOMIC_RELEASE, "agent");
;             asm volatile("s_waitcnt vmcnt(0)" ::: "memory");
;             const unsigned og = xb_add(&bar[XB_TOP], 1u);
;             const unsigned tg = og / nx;
;             if (og + 1u == (tg + 1u) * nx) xb_add(&bar[XB_TOPGEN], 1u);
;             else XB_SPIN(xb_ld(&bar[XB_TOPGEN]) == tg, bar);
;             __builtin_amdgcn_fence(__ATOMIC_ACQUIRE, "agent");
;             xb_add(&bar[XB_XGEN(b.x)], 1u);
;             asm volatile("s_waitcnt vmcnt(0)" ::: "memory");
;         } else {
;             XB_SPIN(xb_ld(&bar[XB_XGEN(b.x)]) == gen, bar);
.LBB0_1288:
	s_or_b64 exec, exec, s[20:21]
	v_cvt_f32_u32_e32 v4, v2
	s_waitcnt vmcnt(0)
	v_readfirstlane_b32 s6, v3
	v_sub_u32_e32 v3, 0, v2
	v_rcp_iflag_f32_e32 v4, v4
	v_add_u32_e32 v5, s6, v1
	v_mul_f32_e32 v4, 0x4f7ffffe, v4
	v_cvt_u32_f32_e32 v4, v4
	v_mul_lo_u32 v1, v3, v4
	v_mul_hi_u32 v1, v4, v1
	v_add_u32_e32 v1, v4, v1
	v_mul_hi_u32 v1, v5, v1
	v_mul_lo_u32 v3, v1, v2
	v_sub_u32_e32 v3, v5, v3
	v_add_u32_e32 v4, 1, v1
	v_cmp_ge_u32_e32 vcc, v3, v2
	s_nop 1
	v_cndmask_b32_e32 v1, v1, v4, vcc
	v_sub_u32_e32 v4, v3, v2
	v_cndmask_b32_e32 v3, v3, v4, vcc
	v_add_u32_e32 v4, 1, v1
	v_cmp_ge_u32_e32 vcc, v3, v2
	v_add_u32_e32 v3, 1, v5
	s_nop 0
	v_cndmask_b32_e32 v1, v1, v4, vcc
	v_mul_lo_u32 v4, v2, v1
	v_add_u32_e32 v2, v4, v2
	v_cmp_ne_u32_e32 vcc, v3, v2
	s_and_saveexec_b64 s[6:7], vcc
	s_xor_b64 s[18:19], exec, s[6:7]
	s_cbranch_execz .LBB0_1302
	s_waitcnt lgkmcnt(0)
	v_add_u32_e32 v3, 1, v1
	v_mul_lo_u32 v3, v3, v0
	v_mov_b32_e32 v0, 0xcb500
	global_load_dword v0, v0, s[14:15] offset:-256 sc1
	s_add_u32 s26, s14, 0xcb500
	s_addc_u32 s27, s15, 0
	s_waitcnt vmcnt(0)
	v_cmp_lt_u32_e32 vcc, v0, v3
	s_and_saveexec_b64 s[20:21], vcc
	s_cbranch_execz .LBB0_1301
	s_add_u32 s22, s14, 0xc8200
	s_addc_u32 s23, s15, 0
	s_mov_b32 s6, 1
	s_mov_b64 s[36:37], 0
	v_mov_b32_e32 v0, 0
	s_branch .LBB0_1292

; __device__ __forceinline__ unsigned xb_ld(unsigned* p)              { return __hip_atomic_load(p, __ATOMIC_RELAXED, __HIP_MEMORY_SCOPE_AGENT); }
; __device__ __forceinline__ unsigned xb_add(unsigned* p, unsigned v) { return __hip_atomic_fetch_add(p, v, __ATOMIC_RELAXED, __HIP_MEMORY_SCOPE_AGENT); }
; #define XB_SPIN(cond, bar) do { unsigned _sp = 0; while (cond) { __builtin_amdgcn_s_sleep(1); \
;     if ((++_sp & 255u) == 0u) { if (xb_ld(&(bar)[XB_TMO])) break; if (_sp > XB_SPIN_CAP) { atomicAdd(&(bar)[XB_TMO], 1u); break; } } } } while (0)
; __device__ __forceinline__ void xcd_barrier(const XcdBarrier& b) {
;     ...
;             const unsigned og = xb_add(&bar[XB_TOP], 1u);
;             const unsigned tg = og / nx;
;             if (og + 1u == (tg + 1u) * nx) xb_add(&bar[XB_TOPGEN], 1u);
;             else XB_SPIN(xb_ld(&bar[XB_TOPGEN]) == tg, bar);
.LBB0_1305:
	s_or_b64 exec, exec, s[20:21]
	v_cvt_f32_u32_e32 v3, v0
	s_waitcnt vmcnt(0)
	v_readfirstlane_b32 s6, v2
	s_add_u32 s20, s14, 0xcb500
	s_addc_u32 s21, s15, 0
	v_rcp_iflag_f32_e32 v3, v3
	v_add_u32_e32 v1, s6, v1
	v_add_u32_e32 v4, 1, v1
	s_mov_b64 s[22:23], -1
	v_mul_f32_e32 v2, 0x4f7ffffe, v3
	v_cvt_u32_f32_e32 v2, v2
	v_sub_u32_e32 v3, 0, v0
	v_mul_lo_u32 v3, v3, v2
	v_mul_hi_u32 v3, v2, v3
	v_add_u32_e32 v2, v2, v3
	v_mul_hi_u32 v2, v1, v2
	v_mul_lo_u32 v3, v2, v0
	v_sub_u32_e32 v1, v1, v3
	v_add_u32_e32 v5, 1, v2
	v_cmp_ge_u32_e32 vcc, v1, v0
	v_sub_u32_e32 v3, v1, v0
	s_nop 0
	v_cndmask_b32_e32 v2, v2, v5, vcc
	v_cndmask_b32_e32 v1, v1, v3, vcc
	v_add_u32_e32 v3, 1, v2
	v_cmp_ge_u32_e32 vcc, v1, v0
	s_nop 1
	v_cndmask_b32_e32 v2, v2, v3, vcc
	v_mul_lo_u32 v1, v0, v2
	v_add_u32_e32 v0, v1, v0
	v_cmp_ne_u32_e32 vcc, v4, v0
	v_mov_b32_e32 v3, v0
	v_mov_b64_e32 v[0:1], s[20:21]
	s_and_saveexec_b64 s[18:19], vcc
	s_cbranch_execz .LBB0_1317
	v_mov_b32_e32 v0, 0
	global_load_dword v1, v0, s[20:21] offset:-256 sc1
	s_mov_b64 s[36:37], 0
	s_waitcnt vmcnt(0)
	v_cmp_lt_u32_e32 vcc, v1, v3
	s_and_saveexec_b64 s[26:27], vcc
	s_cbranch_execz .LBB0_1316
	s_add_u32 s22, s14, 0xc8200
	s_addc_u32 s23, s15, 0
	s_mov_b32 s6, 1
	s_mov_b64 s[14:15], 0
	s_branch .LBB0_1309

; __device__ __forceinline__ unsigned xb_ld(unsigned* p)              { return __hip_atomic_load(p, __ATOMIC_RELAXED, __HIP_MEMORY_SCOPE_AGENT); }
; __device__ __forceinline__ unsigned xb_add(unsigned* p, unsigned v) { return __hip_atomic_fetch_add(p, v, __ATOMIC_RELAXED, __HIP_MEMORY_SCOPE_AGENT); }
; #define XB_SPIN(cond, bar) do { unsigned _sp = 0; while (cond) { __builtin_amdgcn_s_sleep(1); \
;     if ((++_sp & 255u) == 0u) { if (xb_ld(&(bar)[XB_TMO])) break; if (_sp > XB_SPIN_CAP) { atomicAdd(&(bar)[XB_TMO], 1u); break; } } } } while (0)
; __device__ __forceinline__ void xcd_barrier(const XcdBarrier& b) {
;     ...
;         const unsigned old = xb_add(&bar[XB_XSUB(b.x)], 1u);
;         const unsigned gen = old / nloc;
;         if (old + 1u == (gen + 1u) * nloc) {
;             __builtin_amdgcn_fence(__ATOMIC_RELEASE, "agent");
;             asm volatile("s_waitcnt vmcnt(0)" ::: "memory");
;             const unsigned og = xb_add(&bar[XB_TOP], 1u);
;             const unsigned tg = og / nx;
;             if (og + 1u == (tg + 1u) * nx) xb_add(&bar[XB_TOPGEN], 1u);
;             else XB_SPIN(xb_ld(&bar[XB_TOPGEN]) == tg, bar);
;             __builtin_amdgcn_fence(__ATOMIC_ACQUIRE, "agent");
;             xb_add(&bar[XB_XGEN(b.x)], 1u);
;             asm volatile("s_waitcnt vmcnt(0)" ::: "memory");
;         } else {
;             XB_SPIN(xb_ld(&bar[XB_XGEN(b.x)]) == gen, bar);
.LBB0_1508:
	s_or_b64 exec, exec, s[18:19]
	v_cvt_f32_u32_e32 v4, v2
	s_waitcnt vmcnt(0)
	v_readfirstlane_b32 s6, v3
	v_sub_u32_e32 v3, 0, v2
	v_rcp_iflag_f32_e32 v4, v4
	v_add_u32_e32 v5, s6, v1
	v_mul_f32_e32 v4, 0x4f7ffffe, v4
	v_cvt_u32_f32_e32 v4, v4
	v_mul_lo_u32 v1, v3, v4
	v_mul_hi_u32 v1, v4, v1
	v_add_u32_e32 v1, v4, v1
	v_mul_hi_u32 v1, v5, v1
	v_mul_lo_u32 v3, v1, v2
	v_sub_u32_e32 v3, v5, v3
	v_add_u32_e32 v4, 1, v1
	v_cmp_ge_u32_e32 vcc, v3, v2
	s_nop 1
	v_cndmask_b32_e32 v1, v1, v4, vcc
	v_sub_u32_e32 v4, v3, v2
	v_cndmask_b32_e32 v3, v3, v4, vcc
	v_add_u32_e32 v4, 1, v1
	v_cmp_ge_u32_e32 vcc, v3, v2
	v_add_u32_e32 v3, 1, v5
	s_nop 0
	v_cndmask_b32_e32 v1, v1, v4, vcc
	v_mul_lo_u32 v4, v2, v1
	v_add_u32_e32 v2, v4, v2
	v_cmp_ne_u32_e32 vcc, v3, v2
	s_and_saveexec_b64 s[6:7], vcc
	s_xor_b64 s[16:17], exec, s[6:7]
	s_cbranch_execz .LBB0_1522
	s_waitcnt lgkmcnt(0)
	v_add_u32_e32 v3, 1, v1
	v_mul_lo_u32 v3, v3, v0
	v_mov_b32_e32 v0, 0xcb500
	global_load_dword v0, v0, s[12:13] offset:-256 sc1
	s_add_u32 s22, s12, 0xcb500
	s_addc_u32 s23, s13, 0
	s_waitcnt vmcnt(0)
	v_cmp_lt_u32_e32 vcc, v0, v3
	s_and_saveexec_b64 s[18:19], vcc
	s_cbranch_execz .LBB0_1521
	s_add_u32 s20, s12, 0xc8200
	s_addc_u32 s21, s13, 0
	s_mov_b32 s6, 1
	s_mov_b64 s[26:27], 0
	v_mov_b32_e32 v0, 0
	s_branch .LBB0_1512

; __device__ __forceinline__ unsigned xb_ld(unsigned* p)              { return __hip_atomic_load(p, __ATOMIC_RELAXED, __HIP_MEMORY_SCOPE_AGENT); }
; #define XB_SPIN(cond, bar) do { unsigned _sp = 0; while (cond) { __builtin_amdgcn_s_sleep(1); \
;     if ((++_sp & 255u) == 0u) { if (xb_ld(&(bar)[XB_TMO])) break; if (_sp > XB_SPIN_CAP) { atomicAdd(&(bar)[XB_TMO], 1u); break; } } } } while (0)
; __device__ __forceinline__ void xcd_barrier(const XcdBarrier& b) {
;     ...
;             XB_SPIN(xb_ld(&bar[XB_XGEN(b.x)]) == gen, bar);
.LBB0_1516:
	global_load_dword v2, v0, s[22:23] offset:-256 sc1
	s_add_i32 s6, s6, 1
	s_mov_b64 s[40:41], -1
	s_waitcnt vmcnt(0)
	v_cmp_ge_u32_e32 vcc, v2, v3
	s_orn2_b64 s[38:39], vcc, exec
	s_branch .LBB0_1511

; __device__ __forceinline__ unsigned xb_ld(unsigned* p)              { return __hip_atomic_load(p, __ATOMIC_RELAXED, __HIP_MEMORY_SCOPE_AGENT); }
; __device__ __forceinline__ unsigned xb_add(unsigned* p, unsigned v) { return __hip_atomic_fetch_add(p, v, __ATOMIC_RELAXED, __HIP_MEMORY_SCOPE_AGENT); }
; #define XB_SPIN(cond, bar) do { unsigned _sp = 0; while (cond) { __builtin_amdgcn_s_sleep(1); \
;     if ((++_sp & 255u) == 0u) { if (xb_ld(&(bar)[XB_TMO])) break; if (_sp > XB_SPIN_CAP) { atomicAdd(&(bar)[XB_TMO], 1u); break; } } } } while (0)
; __device__ __forceinline__ void xcd_barrier(const XcdBarrier& b) {
;     ...
;             const unsigned og = xb_add(&bar[XB_TOP], 1u);
;             const unsigned tg = og / nx;
;             if (og + 1u == (tg + 1u) * nx) xb_add(&bar[XB_TOPGEN], 1u);
;             else XB_SPIN(xb_ld(&bar[XB_TOPGEN]) == tg, bar);
.LBB0_1525:
	s_or_b64 exec, exec, s[18:19]
	v_cvt_f32_u32_e32 v3, v0
	s_waitcnt vmcnt(0)
	v_readfirstlane_b32 s6, v2
	s_add_u32 s18, s12, 0xcb500
	s_addc_u32 s19, s13, 0
	v_rcp_iflag_f32_e32 v3, v3
	v_add_u32_e32 v1, s6, v1
	v_add_u32_e32 v4, 1, v1
	s_mov_b64 s[20:21], -1
	v_mul_f32_e32 v2, 0x4f7ffffe, v3
	v_cvt_u32_f32_e32 v2, v2
	v_sub_u32_e32 v3, 0, v0
	v_mul_lo_u32 v3, v3, v2
	v_mul_hi_u32 v3, v2, v3
	v_add_u32_e32 v2, v2, v3
	v_mul_hi_u32 v2, v1, v2
	v_mul_lo_u32 v3, v2, v0
	v_sub_u32_e32 v1, v1, v3
	v_add_u32_e32 v5, 1, v2
	v_cmp_ge_u32_e32 vcc, v1, v0
	v_sub_u32_e32 v3, v1, v0
	s_nop 0
	v_cndmask_b32_e32 v2, v2, v5, vcc
	v_cndmask_b32_e32 v1, v1, v3, vcc
	v_add_u32_e32 v3, 1, v2
	v_cmp_ge_u32_e32 vcc, v1, v0
	s_nop 1
	v_cndmask_b32_e32 v2, v2, v3, vcc
	v_mul_lo_u32 v1, v0, v2
	v_add_u32_e32 v0, v1, v0
	v_cmp_ne_u32_e32 vcc, v4, v0
	v_mov_b32_e32 v3, v0
	v_mov_b64_e32 v[0:1], s[18:19]
	s_and_saveexec_b64 s[16:17], vcc
	s_cbranch_execz .LBB0_1537
	v_mov_b32_e32 v0, 0
	global_load_dword v1, v0, s[18:19] offset:-256 sc1
	s_mov_b64 s[26:27], 0
	s_waitcnt vmcnt(0)
	v_cmp_lt_u32_e32 vcc, v1, v3
	s_and_saveexec_b64 s[22:23], vcc
	s_cbranch_execz .LBB0_1536
	s_add_u32 s20, s12, 0xc8200
	s_addc_u32 s21, s13, 0
	s_mov_b32 s6, 1
	s_mov_b64 s[12:13], 0
	s_branch .LBB0_1529

; __device__ __forceinline__ unsigned xb_ld(unsigned* p)              { return __hip_atomic_load(p, __ATOMIC_RELAXED, __HIP_MEMORY_SCOPE_AGENT); }
; #define XB_SPIN(cond, bar) do { unsigned _sp = 0; while (cond) { __builtin_amdgcn_s_sleep(1); \
;     if ((++_sp & 255u) == 0u) { if (xb_ld(&(bar)[XB_TMO])) break; if (_sp > XB_SPIN_CAP) { atomicAdd(&(bar)[XB_TMO], 1u); break; } } } } while (0)
; __device__ __forceinline__ void xcd_barrier(const XcdBarrier& b) {
;     ...
;             else XB_SPIN(xb_ld(&bar[XB_TOPGEN]) == tg, bar);
.LBB0_1533:
	global_load_dword v1, v0, s[18:19] offset:-256 sc1
	s_add_i32 s6, s6, 1
	s_mov_b64 s[36:37], -1
	s_waitcnt vmcnt(0)
	v_cmp_ge_u32_e32 vcc, v1, v3
	s_orn2_b64 s[40:41], vcc, exec
	s_branch .LBB0_1528

; __device__ __forceinline__ unsigned xb_ld(unsigned* p)              { return __hip_atomic_load(p, __ATOMIC_RELAXED, __HIP_MEMORY_SCOPE_AGENT); }
; __device__ __forceinline__ unsigned xb_add(unsigned* p, unsigned v) { return __hip_atomic_fetch_add(p, v, __ATOMIC_RELAXED, __HIP_MEMORY_SCOPE_AGENT); }
; #define XB_SPIN(cond, bar) do { unsigned _sp = 0; while (cond) { __builtin_amdgcn_s_sleep(1); \
;     if ((++_sp & 255u) == 0u) { if (xb_ld(&(bar)[XB_TMO])) break; if (_sp > XB_SPIN_CAP) { atomicAdd(&(bar)[XB_TMO], 1u); break; } } } } while (0)
; __device__ __forceinline__ void xcd_barrier(const XcdBarrier& b) {
;     ...
;         const unsigned old = xb_add(&bar[XB_XSUB(b.x)], 1u);
;         const unsigned gen = old / nloc;
;         if (old + 1u == (gen + 1u) * nloc) {
;             __builtin_amdgcn_fence(__ATOMIC_RELEASE, "agent");
;             asm volatile("s_waitcnt vmcnt(0)" ::: "memory");
;             const unsigned og = xb_add(&bar[XB_TOP], 1u);
;             const unsigned tg = og / nx;
;             if (og + 1u == (tg + 1u) * nx) xb_add(&bar[XB_TOPGEN], 1u);
;             else XB_SPIN(xb_ld(&bar[XB_TOPGEN]) == tg, bar);
;             __builtin_amdgcn_fence(__ATOMIC_ACQUIRE, "agent");
;             xb_add(&bar[XB_XGEN(b.x)], 1u);
;             asm volatile("s_waitcnt vmcnt(0)" ::: "memory");
;         } else {
;             XB_SPIN(xb_ld(&bar[XB_XGEN(b.x)]) == gen, bar);
.LBB0_2116:
	s_or_b64 exec, exec, s[16:17]
	v_cvt_f32_u32_e32 v4, v2
	s_waitcnt vmcnt(0)
	v_readfirstlane_b32 s8, v3
	v_sub_u32_e32 v3, 0, v2
	v_rcp_iflag_f32_e32 v4, v4
	v_add_u32_e32 v5, s8, v1
	v_mul_f32_e32 v4, 0x4f7ffffe, v4
	v_cvt_u32_f32_e32 v4, v4
	v_mul_lo_u32 v1, v3, v4
	v_mul_hi_u32 v1, v4, v1
	v_add_u32_e32 v1, v4, v1
	v_mul_hi_u32 v1, v5, v1
	v_mul_lo_u32 v3, v1, v2
	v_sub_u32_e32 v3, v5, v3
	v_add_u32_e32 v4, 1, v1
	v_cmp_ge_u32_e32 vcc, v3, v2
	s_nop 1
	v_cndmask_b32_e32 v1, v1, v4, vcc
	v_sub_u32_e32 v4, v3, v2
	v_cndmask_b32_e32 v3, v3, v4, vcc
	v_add_u32_e32 v4, 1, v1
	v_cmp_ge_u32_e32 vcc, v3, v2
	v_add_u32_e32 v3, 1, v5
	s_nop 0
	v_cndmask_b32_e32 v1, v1, v4, vcc
	v_mul_lo_u32 v4, v2, v1
	v_add_u32_e32 v2, v4, v2
	v_cmp_ne_u32_e32 vcc, v3, v2
	s_and_saveexec_b64 s[8:9], vcc
	s_xor_b64 s[14:15], exec, s[8:9]
	s_cbranch_execz .LBB0_2130
	s_waitcnt lgkmcnt(0)
	v_add_u32_e32 v3, 1, v1
	v_mul_lo_u32 v3, v3, v0
	v_mov_b32_e32 v0, 0xcb500
	global_load_dword v0, v0, s[10:11] offset:-256 sc1
	s_add_u32 s20, s10, 0xcb500
	s_addc_u32 s21, s11, 0
	s_waitcnt vmcnt(0)
	v_cmp_lt_u32_e32 vcc, v0, v3
	s_and_saveexec_b64 s[16:17], vcc
	s_cbranch_execz .LBB0_2129
	s_add_u32 s18, s10, 0xc8200
	s_addc_u32 s19, s11, 0
	s_mov_b32 s8, 1
	s_mov_b64 s[22:23], 0
	v_mov_b32_e32 v0, 0
	s_branch .LBB0_2120

; __device__ __forceinline__ unsigned xb_ld(unsigned* p)              { return __hip_atomic_load(p, __ATOMIC_RELAXED, __HIP_MEMORY_SCOPE_AGENT); }
; #define XB_SPIN(cond, bar) do { unsigned _sp = 0; while (cond) { __builtin_amdgcn_s_sleep(1); \
;     if ((++_sp & 255u) == 0u) { if (xb_ld(&(bar)[XB_TMO])) break; if (_sp > XB_SPIN_CAP) { atomicAdd(&(bar)[XB_TMO], 1u); break; } } } } while (0)
; __device__ __forceinline__ void xcd_barrier(const XcdBarrier& b) {
;     ...
;             XB_SPIN(xb_ld(&bar[XB_XGEN(b.x)]) == gen, bar);
;             __builtin_amdgcn_fence(__ATOMIC_ACQUIRE, "agent");
.LBB0_2124:
	global_load_dword v2, v0, s[20:21] offset:-256 sc1
	s_add_i32 s8, s8, 1
	s_mov_b64 s[38:39], -1
	s_waitcnt vmcnt(0)
	v_cmp_ge_u32_e32 vcc, v2, v3
	s_orn2_b64 s[36:37], vcc, exec
	s_branch .LBB0_2119

; __device__ __forceinline__ unsigned xb_ld(unsigned* p)              { return __hip_atomic_load(p, __ATOMIC_RELAXED, __HIP_MEMORY_SCOPE_AGENT); }
; __device__ __forceinline__ unsigned xb_add(unsigned* p, unsigned v) { return __hip_atomic_fetch_add(p, v, __ATOMIC_RELAXED, __HIP_MEMORY_SCOPE_AGENT); }
; #define XB_SPIN(cond, bar) do { unsigned _sp = 0; while (cond) { __builtin_amdgcn_s_sleep(1); \
;     if ((++_sp & 255u) == 0u) { if (xb_ld(&(bar)[XB_TMO])) break; if (_sp > XB_SPIN_CAP) { atomicAdd(&(bar)[XB_TMO], 1u); break; } } } } while (0)
; __device__ __forceinline__ void xcd_barrier(const XcdBarrier& b) {
;     ...
;             const unsigned og = xb_add(&bar[XB_TOP], 1u);
;             const unsigned tg = og / nx;
;             if (og + 1u == (tg + 1u) * nx) xb_add(&bar[XB_TOPGEN], 1u);
;             else XB_SPIN(xb_ld(&bar[XB_TOPGEN]) == tg, bar);
;             __builtin_amdgcn_fence(__ATOMIC_ACQUIRE, "agent");
.LBB0_2133:
	s_or_b64 exec, exec, s[16:17]
	v_cvt_f32_u32_e32 v3, v0
	s_waitcnt vmcnt(0)
	v_readfirstlane_b32 s8, v2
	s_add_u32 s16, s10, 0xcb500
	s_addc_u32 s17, s11, 0
	v_rcp_iflag_f32_e32 v3, v3
	v_add_u32_e32 v1, s8, v1
	v_add_u32_e32 v4, 1, v1
	s_mov_b64 s[18:19], -1
	v_mul_f32_e32 v2, 0x4f7ffffe, v3
	v_cvt_u32_f32_e32 v2, v2
	v_sub_u32_e32 v3, 0, v0
	v_mul_lo_u32 v3, v3, v2
	v_mul_hi_u32 v3, v2, v3
	v_add_u32_e32 v2, v2, v3
	v_mul_hi_u32 v2, v1, v2
	v_mul_lo_u32 v3, v2, v0
	v_sub_u32_e32 v1, v1, v3
	v_add_u32_e32 v5, 1, v2
	v_cmp_ge_u32_e32 vcc, v1, v0
	v_sub_u32_e32 v3, v1, v0
	s_nop 0
	v_cndmask_b32_e32 v2, v2, v5, vcc
	v_cndmask_b32_e32 v1, v1, v3, vcc
	v_add_u32_e32 v3, 1, v2
	v_cmp_ge_u32_e32 vcc, v1, v0
	s_nop 1
	v_cndmask_b32_e32 v2, v2, v3, vcc
	v_mul_lo_u32 v1, v0, v2
	v_add_u32_e32 v0, v1, v0
	v_cmp_ne_u32_e32 vcc, v4, v0
	v_mov_b32_e32 v3, v0
	v_mov_b64_e32 v[0:1], s[16:17]
	s_and_saveexec_b64 s[14:15], vcc
	s_cbranch_execz .LBB0_2145
	v_mov_b32_e32 v0, 0
	global_load_dword v1, v0, s[16:17] offset:-256 sc1
	s_mov_b64 s[22:23], 0
	s_waitcnt vmcnt(0)
	v_cmp_lt_u32_e32 vcc, v1, v3
	s_and_saveexec_b64 s[20:21], vcc
	s_cbranch_execz .LBB0_2144
	s_add_u32 s18, s10, 0xc8200
	s_addc_u32 s19, s11, 0
	s_mov_b32 s8, 1
	s_mov_b64 s[10:11], 0
	s_branch .LBB0_2137

; __device__ __forceinline__ unsigned xb_ld(unsigned* p)              { return __hip_atomic_load(p, __ATOMIC_RELAXED, __HIP_MEMORY_SCOPE_AGENT); }
; #define XB_SPIN(cond, bar) do { unsigned _sp = 0; while (cond) { __builtin_amdgcn_s_sleep(1); \
;     if ((++_sp & 255u) == 0u) { if (xb_ld(&(bar)[XB_TMO])) break; if (_sp > XB_SPIN_CAP) { atomicAdd(&(bar)[XB_TMO], 1u); break; } } } } while (0)
; __device__ __forceinline__ void xcd_barrier(const XcdBarrier& b) {
;     ...
;             else XB_SPIN(xb_ld(&bar[XB_TOPGEN]) == tg, bar);
.LBB0_2141:
	global_load_dword v1, v0, s[16:17] offset:-256 sc1
	s_add_i32 s8, s8, 1
	s_mov_b64 s[26:27], -1
	s_waitcnt vmcnt(0)
	v_cmp_ge_u32_e32 vcc, v1, v3
	s_orn2_b64 s[38:39], vcc, exec
	s_branch .LBB0_2136

; __device__ __forceinline__ unsigned xb_ld(unsigned* p)              { return __hip_atomic_load(p, __ATOMIC_RELAXED, __HIP_MEMORY_SCOPE_AGENT); }
; __device__ __forceinline__ unsigned xb_add(unsigned* p, unsigned v) { return __hip_atomic_fetch_add(p, v, __ATOMIC_RELAXED, __HIP_MEMORY_SCOPE_AGENT); }
; #define XB_SPIN(cond, bar) do { unsigned _sp = 0; while (cond) { __builtin_amdgcn_s_sleep(1); \
;     if ((++_sp & 255u) == 0u) { if (xb_ld(&(bar)[XB_TMO])) break; if (_sp > XB_SPIN_CAP) { atomicAdd(&(bar)[XB_TMO], 1u); break; } } } } while (0)
; __device__ __forceinline__ void xcd_barrier(const XcdBarrier& b) {
;     ...
;         const unsigned old = xb_add(&bar[XB_XSUB(b.x)], 1u);
;         const unsigned gen = old / nloc;
;         if (old + 1u == (gen + 1u) * nloc) {
;             __builtin_amdgcn_fence(__ATOMIC_RELEASE, "agent");
;             asm volatile("s_waitcnt vmcnt(0)" ::: "memory");
;             const unsigned og = xb_add(&bar[XB_TOP], 1u);
;             const unsigned tg = og / nx;
;             if (og + 1u == (tg + 1u) * nx) xb_add(&bar[XB_TOPGEN], 1u);
;             else XB_SPIN(xb_ld(&bar[XB_TOPGEN]) == tg, bar);
;             __builtin_amdgcn_fence(__ATOMIC_ACQUIRE, "agent");
;             xb_add(&bar[XB_XGEN(b.x)], 1u);
;             asm volatile("s_waitcnt vmcnt(0)" ::: "memory");
;         } else {
;             XB_SPIN(xb_ld(&bar[XB_XGEN(b.x)]) == gen, bar);
.LBB0_2217:
	s_or_b64 exec, exec, s[14:15]
	v_cvt_f32_u32_e32 v4, v2
	s_waitcnt vmcnt(0)
	v_readfirstlane_b32 s12, v3
	v_sub_u32_e32 v3, 0, v2
	v_rcp_iflag_f32_e32 v4, v4
	v_add_u32_e32 v5, s12, v1
	v_mul_f32_e32 v4, 0x4f7ffffe, v4
	v_cvt_u32_f32_e32 v4, v4
	v_mul_lo_u32 v1, v3, v4
	v_mul_hi_u32 v1, v4, v1
	v_add_u32_e32 v1, v4, v1
	v_mul_hi_u32 v1, v5, v1
	v_mul_lo_u32 v3, v1, v2
	v_sub_u32_e32 v3, v5, v3
	v_add_u32_e32 v4, 1, v1
	v_cmp_ge_u32_e32 vcc, v3, v2
	s_nop 1
	v_cndmask_b32_e32 v1, v1, v4, vcc
	v_sub_u32_e32 v4, v3, v2
	v_cndmask_b32_e32 v3, v3, v4, vcc
	v_add_u32_e32 v4, 1, v1
	v_cmp_ge_u32_e32 vcc, v3, v2
	v_add_u32_e32 v3, 1, v5
	s_nop 0
	v_cndmask_b32_e32 v1, v1, v4, vcc
	v_mul_lo_u32 v4, v2, v1
	v_add_u32_e32 v2, v4, v2
	v_cmp_ne_u32_e32 vcc, v3, v2
	s_and_saveexec_b64 s[12:13], vcc
	s_xor_b64 s[12:13], exec, s[12:13]
	s_cbranch_execz .LBB0_2231
	s_waitcnt lgkmcnt(0)
	v_add_u32_e32 v3, 1, v1
	v_mul_lo_u32 v3, v3, v0
	v_mov_b32_e32 v0, 0xcb500
	global_load_dword v0, v0, s[8:9] offset:-256 sc1
	s_add_u32 s18, s8, 0xcb500
	s_addc_u32 s19, s9, 0
	s_waitcnt vmcnt(0)
	v_cmp_lt_u32_e32 vcc, v0, v3
	s_and_saveexec_b64 s[14:15], vcc
	s_cbranch_execz .LBB0_2230
	s_add_u32 s16, s8, 0xc8200
	s_addc_u32 s17, s9, 0
	s_mov_b32 s29, 1
	s_mov_b64 s[20:21], 0
	v_mov_b32_e32 v0, 0
	s_branch .LBB0_2221

; __device__ __forceinline__ unsigned xb_ld(unsigned* p)              { return __hip_atomic_load(p, __ATOMIC_RELAXED, __HIP_MEMORY_SCOPE_AGENT); }
; #define XB_SPIN(cond, bar) do { unsigned _sp = 0; while (cond) { __builtin_amdgcn_s_sleep(1); \
;     if ((++_sp & 255u) == 0u) { if (xb_ld(&(bar)[XB_TMO])) break; if (_sp > XB_SPIN_CAP) { atomicAdd(&(bar)[XB_TMO], 1u); break; } } } } while (0)
; __device__ __forceinline__ void xcd_barrier(const XcdBarrier& b) {
;     ...
;             XB_SPIN(xb_ld(&bar[XB_XGEN(b.x)]) == gen, bar);
;             __builtin_amdgcn_fence(__ATOMIC_ACQUIRE, "agent");
.LBB0_2225:
	global_load_dword v2, v0, s[18:19] offset:-256 sc1
	s_add_i32 s29, s29, 1
	s_mov_b64 s[36:37], -1
	s_waitcnt vmcnt(0)
	v_cmp_ge_u32_e32 vcc, v2, v3
	s_orn2_b64 s[26:27], vcc, exec
	s_branch .LBB0_2220

; __device__ __forceinline__ unsigned xb_ld(unsigned* p)              { return __hip_atomic_load(p, __ATOMIC_RELAXED, __HIP_MEMORY_SCOPE_AGENT); }
; __device__ __forceinline__ unsigned xb_add(unsigned* p, unsigned v) { return __hip_atomic_fetch_add(p, v, __ATOMIC_RELAXED, __HIP_MEMORY_SCOPE_AGENT); }
; #define XB_SPIN(cond, bar) do { unsigned _sp = 0; while (cond) { __builtin_amdgcn_s_sleep(1); \
;     if ((++_sp & 255u) == 0u) { if (xb_ld(&(bar)[XB_TMO])) break; if (_sp > XB_SPIN_CAP) { atomicAdd(&(bar)[XB_TMO], 1u); break; } } } } while (0)
; __device__ __forceinline__ void xcd_barrier(const XcdBarrier& b) {
;     ...
;             const unsigned og = xb_add(&bar[XB_TOP], 1u);
;             const unsigned tg = og / nx;
;             if (og + 1u == (tg + 1u) * nx) xb_add(&bar[XB_TOPGEN], 1u);
;             else XB_SPIN(xb_ld(&bar[XB_TOPGEN]) == tg, bar);
;             __builtin_amdgcn_fence(__ATOMIC_ACQUIRE, "agent");
.LBB0_2234:
	s_or_b64 exec, exec, s[14:15]
	v_cvt_f32_u32_e32 v3, v0
	s_waitcnt vmcnt(0)
	v_readfirstlane_b32 s12, v2
	s_add_u32 s14, s8, 0xcb500
	s_addc_u32 s15, s9, 0
	v_rcp_iflag_f32_e32 v3, v3
	v_add_u32_e32 v1, s12, v1
	v_add_u32_e32 v4, 1, v1
	s_mov_b64 s[16:17], -1
	v_mul_f32_e32 v2, 0x4f7ffffe, v3
	v_cvt_u32_f32_e32 v2, v2
	v_sub_u32_e32 v3, 0, v0
	v_mul_lo_u32 v3, v3, v2
	v_mul_hi_u32 v3, v2, v3
	v_add_u32_e32 v2, v2, v3
	v_mul_hi_u32 v2, v1, v2
	v_mul_lo_u32 v3, v2, v0
	v_sub_u32_e32 v1, v1, v3
	v_add_u32_e32 v5, 1, v2
	v_cmp_ge_u32_e32 vcc, v1, v0
	v_sub_u32_e32 v3, v1, v0
	s_nop 0
	v_cndmask_b32_e32 v2, v2, v5, vcc
	v_cndmask_b32_e32 v1, v1, v3, vcc
	v_add_u32_e32 v3, 1, v2
	v_cmp_ge_u32_e32 vcc, v1, v0
	s_nop 1
	v_cndmask_b32_e32 v2, v2, v3, vcc
	v_mul_lo_u32 v1, v0, v2
	v_add_u32_e32 v0, v1, v0
	v_cmp_ne_u32_e32 vcc, v4, v0
	v_mov_b32_e32 v3, v0
	v_mov_b64_e32 v[0:1], s[14:15]
	s_and_saveexec_b64 s[12:13], vcc
	s_cbranch_execz .LBB0_2246
	v_mov_b32_e32 v0, 0
	global_load_dword v1, v0, s[14:15] offset:-256 sc1
	s_mov_b64 s[20:21], 0
	s_waitcnt vmcnt(0)
	v_cmp_lt_u32_e32 vcc, v1, v3
	s_and_saveexec_b64 s[18:19], vcc
	s_cbranch_execz .LBB0_2245
	s_add_u32 s16, s8, 0xc8200
	s_addc_u32 s17, s9, 0
	s_mov_b32 s29, 1
	s_mov_b64 s[8:9], 0
	s_branch .LBB0_2238

; __device__ __forceinline__ unsigned xb_ld(unsigned* p)              { return __hip_atomic_load(p, __ATOMIC_RELAXED, __HIP_MEMORY_SCOPE_AGENT); }
; #define XB_SPIN(cond, bar) do { unsigned _sp = 0; while (cond) { __builtin_amdgcn_s_sleep(1); \
;     if ((++_sp & 255u) == 0u) { if (xb_ld(&(bar)[XB_TMO])) break; if (_sp > XB_SPIN_CAP) { atomicAdd(&(bar)[XB_TMO], 1u); break; } } } } while (0)
; __device__ __forceinline__ void xcd_barrier(const XcdBarrier& b) {
;     ...
;             else XB_SPIN(xb_ld(&bar[XB_TOPGEN]) == tg, bar);
.LBB0_2242:
	global_load_dword v1, v0, s[14:15] offset:-256 sc1
	s_add_i32 s29, s29, 1
	s_mov_b64 s[22:23], -1
	s_waitcnt vmcnt(0)
	v_cmp_ge_u32_e32 vcc, v1, v3
	s_orn2_b64 s[36:37], vcc, exec
	s_branch .LBB0_2237

; __device__ __forceinline__ unsigned xb_ld(unsigned* p)              { return __hip_atomic_load(p, __ATOMIC_RELAXED, __HIP_MEMORY_SCOPE_AGENT); }
; #define XB_SPIN(cond, bar) do { unsigned _sp = 0; while (cond) { __builtin_amdgcn_s_sleep(1); \
;     if ((++_sp & 255u) == 0u) { if (xb_ld(&(bar)[XB_TMO])) break; if (_sp > XB_SPIN_CAP) { atomicAdd(&(bar)[XB_TMO], 1u); break; } } } } while (0)
; __device__ __forceinline__ void xcd_barrier(const XcdBarrier& b) {
;     ...
;             XB_SPIN(xb_ld(&bar[XB_XGEN(b.x)]) == gen, bar);
;             __builtin_amdgcn_fence(__ATOMIC_ACQUIRE, "agent");
.LBB0_2494:
	global_load_dword v2, v0, s[18:19] offset:-256 sc1
	s_add_i32 s29, s29, 1
	s_mov_b64 s[34:35], -1
	s_waitcnt vmcnt(0)
	v_cmp_ge_u32_e32 vcc, v2, v3
	s_orn2_b64 s[26:27], vcc, exec
	s_branch .LBB0_2489

; __device__ __forceinline__ unsigned xb_ld(unsigned* p)              { return __hip_atomic_load(p, __ATOMIC_RELAXED, __HIP_MEMORY_SCOPE_AGENT); }
; #define XB_SPIN(cond, bar) do { unsigned _sp = 0; while (cond) { __builtin_amdgcn_s_sleep(1); \
;     if ((++_sp & 255u) == 0u) { if (xb_ld(&(bar)[XB_TMO])) break; if (_sp > XB_SPIN_CAP) { atomicAdd(&(bar)[XB_TMO], 1u); break; } } } } while (0)
; __device__ __forceinline__ void xcd_barrier(const XcdBarrier& b) {
;     ...
;             else XB_SPIN(xb_ld(&bar[XB_TOPGEN]) == tg, bar);
.LBB0_2511:
	global_load_dword v1, v0, s[14:15] offset:-256 sc1
	s_add_i32 s29, s29, 1
	s_mov_b64 s[22:23], -1
	s_waitcnt vmcnt(0)
	v_cmp_ge_u32_e32 vcc, v1, v3
	s_orn2_b64 s[34:35], vcc, exec
	s_branch .LBB0_2506
